# mixer first items permuted so query blocks sharing K/V run on the same XCD (L2 reuse)
# baseline (speedup 1.0000x reference)
.LBB0_164:
	s_andn2_b64 vcc, exec, s[0:1]
	s_cbranch_vccnz .LBB0_329
	s_lshl_b32 s0, s38, 6
	s_ashr_i32 s1, s0, 31
	s_lshl_b64 s[0:1], s[0:1], 2
	v_readlane_b32 s2, v249, 61
	s_add_u32 s2, s2, s0
	v_readlane_b32 s0, v249, 62
	s_addc_u32 s3, s0, s1
	v_writelane_b32 v247, s2, 49
	s_ashr_i32 s39, s38, 31
	s_lshl_b64 s[0:1], s[38:39], 14
	v_writelane_b32 v247, s3, 50
	v_writelane_b32 v247, s0, 51
	s_mov_b64 s[4:5], 0
	s_nop 0
	v_writelane_b32 v247, s1, 52
	s_lshl_b32 s0, s38, 8
	v_writelane_b32 v247, s0, 53
	s_mov_b32 s0, s38
	v_writelane_b32 v247, s0, 54
	s_nop 1
	v_writelane_b32 v247, s1, 55
	s_lshl_b32 s0, s38, 3
	v_writelane_b32 v247, s0, 56
	v_readlane_b32 s0, v249, 0
	s_waitcnt vmcnt(0) lgkmcnt(0)
	s_nop 0
	v_readlane_b32 s2, v249, 7
	v_readlane_b32 s3, v249, 8
	s_load_dword s1, s[2:3], 0x0
	s_waitcnt lgkmcnt(0)
	s_cmpk_eq_u32 s1, 0x200
	s_cbranch_scc0 .Lmx_done
	s_and_b32 s2, s0, 7
	s_cmpk_lt_u32 s0, 0x100
	s_cbranch_scc0 .Lmx_k0
	s_and_b32 s1, s0, 0xc0
	s_lshl_b32 s2, s2, 3
	s_bfe_u32 s3, s0, 0x30003
	s_or_b32 s1, s1, s2
	s_or_b32 s0, s1, s3
	s_branch .Lmx_done
.Lmx_k0:
	s_bfe_u32 s3, s0, 0x50003
	s_lshl_b32 s2, s2, 5
	s_or_b32 s2, s2, s3
	s_or_b32 s0, s2, 0x100
.Lmx_done:
	v_mov_b32_e32 v0, s0
	s_branch .LBB0_169
